# P1/P4 k-loops only: every read phase issues all its fragment ds_reads first; next-unit pointer selects, DMA address adds and M0 writes follow
# speedup vs baseline: 1.0028x; 1.0009x over previous
.LBB0_146:
	ds_read_b128 v[128:131], v188
	ds_read_b128 v[132:135], v188 offset:1024
	ds_read_b128 v[136:139], v188 offset:2048
	ds_read_b128 v[140:143], v188 offset:3072
	ds_read_b128 v[144:147], v189
	ds_read_b128 v[148:151], v189 offset:1024
	ds_read_b128 v[176:179], v189 offset:2048
	ds_read_b128 v[180:183], v189 offset:3072
	ds_read_b128 v[194:197], v190
	ds_read_b128 v[198:201], v190 offset:1024
	ds_read_b128 v[202:205], v190 offset:2048
	ds_read_b128 v[206:209], v190 offset:3072
	ds_read_b128 v[210:213], v190 offset:4096
	ds_read_b128 v[214:217], v190 offset:5120
	ds_read_b128 v[218:221], v190 offset:6144
	ds_read_b128 v[222:225], v190 offset:7168
	s_add_u32 s50, s48, 0x100
	s_addc_u32 s51, s49, 0
	s_cmp_eq_u32 s57, 28
	s_cselect_b32 s55, s21, s51
	s_cselect_b32 s54, s20, s50
	s_cselect_b32 s53, s23, s56
	s_cselect_b32 s52, s22, s27
	s_add_i32 m0, s60, 0xc000
	v_lshl_add_u64 v[184:185], s[48:49], 0, v[170:171]
	global_load_lds_dwordx4 v[184:185], off
	v_lshl_add_u64 v[184:185], s[48:49], 0, v[172:173]
	s_add_i32 m0, s60, 0xe000
	s_nop 0
	global_load_lds_dwordx4 v[184:185], off
	s_waitcnt vmcnt(8) lgkmcnt(0)
	s_setprio 1
	s_barrier
	v_mfma_f32_16x16x32_bf16 v[120:123], v[128:131], v[194:197], v[120:123]
	v_mfma_f32_16x16x32_bf16 v[124:127], v[136:139], v[194:197], v[124:127]
	v_mfma_f32_16x16x32_bf16 v[108:111], v[128:131], v[202:205], v[108:111]
	v_mfma_f32_16x16x32_bf16 v[104:107], v[136:139], v[202:205], v[104:107]
	v_mfma_f32_16x16x32_bf16 v[92:95], v[128:131], v[210:213], v[92:95]
	v_mfma_f32_16x16x32_bf16 v[88:91], v[136:139], v[210:213], v[88:91]
	v_mfma_f32_16x16x32_bf16 v[76:79], v[128:131], v[218:221], v[76:79]
	v_mfma_f32_16x16x32_bf16 v[72:75], v[136:139], v[218:221], v[72:75]
	v_mfma_f32_16x16x32_bf16 v[120:123], v[132:135], v[198:201], v[120:123]
	v_mfma_f32_16x16x32_bf16 v[124:127], v[140:143], v[198:201], v[124:127]
	v_mfma_f32_16x16x32_bf16 v[108:111], v[132:135], v[206:209], v[108:111]
	v_mfma_f32_16x16x32_bf16 v[104:107], v[140:143], v[206:209], v[104:107]
	v_mfma_f32_16x16x32_bf16 v[92:95], v[132:135], v[214:217], v[92:95]
	v_mfma_f32_16x16x32_bf16 v[88:91], v[140:143], v[214:217], v[88:91]
	v_mfma_f32_16x16x32_bf16 v[76:79], v[132:135], v[222:225], v[76:79]
	v_mfma_f32_16x16x32_bf16 v[72:75], v[140:143], v[222:225], v[72:75]
	s_setprio 0
	s_setprio 1
	v_mfma_f32_16x16x32_bf16 v[112:115], v[144:147], v[194:197], v[112:115]
	v_mfma_f32_16x16x32_bf16 v[116:119], v[176:179], v[194:197], v[116:119]
	v_mfma_f32_16x16x32_bf16 v[100:103], v[144:147], v[202:205], v[100:103]
	v_mfma_f32_16x16x32_bf16 v[96:99], v[176:179], v[202:205], v[96:99]
	v_mfma_f32_16x16x32_bf16 v[84:87], v[144:147], v[210:213], v[84:87]
	v_mfma_f32_16x16x32_bf16 v[80:83], v[176:179], v[210:213], v[80:83]
	v_mfma_f32_16x16x32_bf16 v[68:71], v[144:147], v[218:221], v[68:71]
	v_mfma_f32_16x16x32_bf16 v[64:67], v[176:179], v[218:221], v[64:67]
	v_mfma_f32_16x16x32_bf16 v[112:115], v[148:151], v[198:201], v[112:115]
	v_mfma_f32_16x16x32_bf16 v[116:119], v[180:183], v[198:201], v[116:119]
	v_mfma_f32_16x16x32_bf16 v[100:103], v[148:151], v[206:209], v[100:103]
	v_mfma_f32_16x16x32_bf16 v[96:99], v[180:183], v[206:209], v[96:99]
	v_mfma_f32_16x16x32_bf16 v[84:87], v[148:151], v[214:217], v[84:87]
	v_mfma_f32_16x16x32_bf16 v[80:83], v[180:183], v[214:217], v[80:83]
	v_mfma_f32_16x16x32_bf16 v[68:71], v[148:151], v[222:225], v[68:71]
	v_mfma_f32_16x16x32_bf16 v[64:67], v[180:183], v[222:225], v[64:67]
	s_barrier
	ds_read_b128 v[194:197], v190 offset:16384
	ds_read_b128 v[198:201], v190 offset:17408
	ds_read_b128 v[202:205], v190 offset:18432
	ds_read_b128 v[206:209], v190 offset:19456
	ds_read_b128 v[210:213], v190 offset:20480
	ds_read_b128 v[214:217], v190 offset:21504
	ds_read_b128 v[218:221], v190 offset:22528
	ds_read_b128 v[222:225], v190 offset:23552
	s_setprio 0
	s_add_i32 s48, s71, s3
	s_mov_b32 m0, s48
	v_lshl_add_u64 v[184:185], s[52:53], 0, v[154:155]
	global_load_lds_dwordx4 v[184:185], off
	s_add_i32 m0, s48, 0x2000
	s_add_u32 s48, s52, 0x80000
	v_lshl_add_u64 v[226:227], s[52:53], 0, v[158:159]
	s_addc_u32 s49, s53, 0
	s_add_i32 s58, s72, s3
	global_load_lds_dwordx4 v[226:227], off
	v_lshl_add_u64 v[228:229], s[48:49], 0, v[154:155]
	s_mov_b32 m0, s58
	v_lshl_add_u64 v[230:231], s[54:55], 0, v[156:157]
	global_load_lds_dwordx4 v[228:229], off
	v_lshl_add_u64 v[228:229], s[48:49], 0, v[158:159]
	s_add_i32 m0, s58, 0x2000
	s_nop 0
	global_load_lds_dwordx4 v[228:229], off
	v_lshl_add_u64 v[228:229], s[54:55], 0, v[152:153]
	s_mov_b32 m0, s60
	s_nop 0
	global_load_lds_dwordx4 v[228:229], off
	s_mov_b32 m0, s61
	s_nop 0
	global_load_lds_dwordx4 v[230:231], off
	s_waitcnt vmcnt(8) lgkmcnt(0)
	s_setprio 1
	s_barrier
	v_mfma_f32_16x16x32_bf16 v[60:63], v[128:131], v[194:197], v[60:63]
	v_mfma_f32_16x16x32_bf16 v[56:59], v[136:139], v[194:197], v[56:59]
	v_mfma_f32_16x16x32_bf16 v[44:47], v[128:131], v[202:205], v[44:47]
	v_mfma_f32_16x16x32_bf16 v[40:43], v[136:139], v[202:205], v[40:43]
	v_mfma_f32_16x16x32_bf16 v[28:31], v[128:131], v[210:213], v[28:31]
	v_mfma_f32_16x16x32_bf16 v[24:27], v[136:139], v[210:213], v[24:27]
	v_mfma_f32_16x16x32_bf16 v[12:15], v[128:131], v[218:221], v[12:15]
	v_mfma_f32_16x16x32_bf16 v[8:11], v[136:139], v[218:221], v[8:11]
	v_mfma_f32_16x16x32_bf16 v[60:63], v[132:135], v[198:201], v[60:63]
	v_mfma_f32_16x16x32_bf16 v[56:59], v[140:143], v[198:201], v[56:59]
	v_mfma_f32_16x16x32_bf16 v[44:47], v[132:135], v[206:209], v[44:47]
	v_mfma_f32_16x16x32_bf16 v[40:43], v[140:143], v[206:209], v[40:43]
	v_mfma_f32_16x16x32_bf16 v[28:31], v[132:135], v[214:217], v[28:31]
	v_mfma_f32_16x16x32_bf16 v[24:27], v[140:143], v[214:217], v[24:27]
	v_mfma_f32_16x16x32_bf16 v[12:15], v[132:135], v[222:225], v[12:15]
	v_mfma_f32_16x16x32_bf16 v[8:11], v[140:143], v[222:225], v[8:11]
	s_setprio 0
	s_setprio 1
	v_mfma_f32_16x16x32_bf16 v[52:55], v[144:147], v[194:197], v[52:55]
	v_mfma_f32_16x16x32_bf16 v[48:51], v[176:179], v[194:197], v[48:51]
	v_mfma_f32_16x16x32_bf16 v[36:39], v[144:147], v[202:205], v[36:39]
	v_mfma_f32_16x16x32_bf16 v[32:35], v[176:179], v[202:205], v[32:35]
	v_mfma_f32_16x16x32_bf16 v[20:23], v[144:147], v[210:213], v[20:23]
	v_mfma_f32_16x16x32_bf16 v[16:19], v[176:179], v[210:213], v[16:19]
	v_mfma_f32_16x16x32_bf16 v[4:7], v[144:147], v[218:221], v[4:7]
	v_mfma_f32_16x16x32_bf16 v[0:3], v[176:179], v[218:221], v[0:3]
	v_mfma_f32_16x16x32_bf16 v[52:55], v[148:151], v[198:201], v[52:55]
	v_mfma_f32_16x16x32_bf16 v[48:51], v[180:183], v[198:201], v[48:51]
	v_mfma_f32_16x16x32_bf16 v[36:39], v[148:151], v[206:209], v[36:39]
	v_mfma_f32_16x16x32_bf16 v[32:35], v[180:183], v[206:209], v[32:35]
	v_mfma_f32_16x16x32_bf16 v[20:23], v[148:151], v[214:217], v[20:23]
	v_mfma_f32_16x16x32_bf16 v[16:19], v[180:183], v[214:217], v[16:19]
	v_mfma_f32_16x16x32_bf16 v[4:7], v[148:151], v[222:225], v[4:7]
	v_mfma_f32_16x16x32_bf16 v[0:3], v[180:183], v[222:225], v[0:3]
	s_barrier
	s_setprio 0
.Lpeel_mid_p1:
	s_add_i32 s58, 0, 0x18000
	s_add_i32 s59, 0, 0x1c000
	v_add_u32_e32 v140, s58, v186
	v_add_u32_e32 v160, s59, v186
	ds_read_b128 v[128:131], v140
	ds_read_b128 v[132:135], v140 offset:1024
	ds_read_b128 v[136:139], v140 offset:2048
	ds_read_b128 v[140:143], v140 offset:3072
	ds_read_b128 v[144:147], v160
	ds_read_b128 v[148:151], v160 offset:1024
	ds_read_b128 v[176:179], v160 offset:2048
	ds_read_b128 v[180:183], v160 offset:3072
	s_add_u32 s48, s54, 0xa0000
	s_addc_u32 s49, s55, 0
	s_mov_b32 m0, s62
	v_lshl_add_u64 v[232:233], s[48:49], 0, v[152:153]
	ds_read_b128 v[194:197], v190 offset:32768
	ds_read_b128 v[198:201], v190 offset:33792
	ds_read_b128 v[202:205], v190 offset:34816
	ds_read_b128 v[206:209], v190 offset:35840
	ds_read_b128 v[210:213], v190 offset:36864
	ds_read_b128 v[214:217], v190 offset:37888
	ds_read_b128 v[218:221], v190 offset:38912
	ds_read_b128 v[222:225], v190 offset:39936
	global_load_lds_dwordx4 v[232:233], off
	v_lshl_add_u64 v[232:233], s[48:49], 0, v[156:157]
	s_mov_b32 m0, s63
	s_nop 0
	global_load_lds_dwordx4 v[232:233], off
	s_waitcnt vmcnt(8) lgkmcnt(0)
	s_setprio 1
	s_barrier
	v_mfma_f32_16x16x32_bf16 v[120:123], v[128:131], v[194:197], v[120:123]
	v_mfma_f32_16x16x32_bf16 v[124:127], v[136:139], v[194:197], v[124:127]
	v_mfma_f32_16x16x32_bf16 v[108:111], v[128:131], v[202:205], v[108:111]
	v_mfma_f32_16x16x32_bf16 v[104:107], v[136:139], v[202:205], v[104:107]
	v_mfma_f32_16x16x32_bf16 v[92:95], v[128:131], v[210:213], v[92:95]
	v_mfma_f32_16x16x32_bf16 v[88:91], v[136:139], v[210:213], v[88:91]
	v_mfma_f32_16x16x32_bf16 v[76:79], v[128:131], v[218:221], v[76:79]
	v_mfma_f32_16x16x32_bf16 v[72:75], v[136:139], v[218:221], v[72:75]
	v_mfma_f32_16x16x32_bf16 v[120:123], v[132:135], v[198:201], v[120:123]
	v_mfma_f32_16x16x32_bf16 v[124:127], v[140:143], v[198:201], v[124:127]
	v_mfma_f32_16x16x32_bf16 v[108:111], v[132:135], v[206:209], v[108:111]
	v_mfma_f32_16x16x32_bf16 v[104:107], v[140:143], v[206:209], v[104:107]
	v_mfma_f32_16x16x32_bf16 v[92:95], v[132:135], v[214:217], v[92:95]
	v_mfma_f32_16x16x32_bf16 v[88:91], v[140:143], v[214:217], v[88:91]
	v_mfma_f32_16x16x32_bf16 v[76:79], v[132:135], v[222:225], v[76:79]
	v_mfma_f32_16x16x32_bf16 v[72:75], v[140:143], v[222:225], v[72:75]
	s_setprio 0
	s_setprio 1
	v_mfma_f32_16x16x32_bf16 v[112:115], v[144:147], v[194:197], v[112:115]
	v_mfma_f32_16x16x32_bf16 v[116:119], v[176:179], v[194:197], v[116:119]
	v_mfma_f32_16x16x32_bf16 v[100:103], v[144:147], v[202:205], v[100:103]
	v_mfma_f32_16x16x32_bf16 v[96:99], v[176:179], v[202:205], v[96:99]
	v_mfma_f32_16x16x32_bf16 v[84:87], v[144:147], v[210:213], v[84:87]
	v_mfma_f32_16x16x32_bf16 v[80:83], v[176:179], v[210:213], v[80:83]
	v_mfma_f32_16x16x32_bf16 v[68:71], v[144:147], v[218:221], v[68:71]
	v_mfma_f32_16x16x32_bf16 v[64:67], v[176:179], v[218:221], v[64:67]
	v_mfma_f32_16x16x32_bf16 v[112:115], v[148:151], v[198:201], v[112:115]
	v_mfma_f32_16x16x32_bf16 v[116:119], v[180:183], v[198:201], v[116:119]
	v_mfma_f32_16x16x32_bf16 v[100:103], v[148:151], v[206:209], v[100:103]
	v_mfma_f32_16x16x32_bf16 v[96:99], v[180:183], v[206:209], v[96:99]
	v_mfma_f32_16x16x32_bf16 v[84:87], v[148:151], v[214:217], v[84:87]
	v_mfma_f32_16x16x32_bf16 v[80:83], v[180:183], v[214:217], v[80:83]
	v_mfma_f32_16x16x32_bf16 v[68:71], v[148:151], v[222:225], v[68:71]
	v_mfma_f32_16x16x32_bf16 v[64:67], v[180:183], v[222:225], v[64:67]
	s_barrier
	ds_read_b128 v[194:197], v190 offset:49152
	ds_read_b128 v[198:201], v190 offset:50176
	ds_read_b128 v[202:205], v190 offset:51200
	ds_read_b128 v[206:209], v190 offset:52224
	ds_read_b128 v[210:213], v190 offset:53248
	ds_read_b128 v[214:217], v190 offset:54272
	ds_read_b128 v[218:221], v190 offset:55296
	ds_read_b128 v[222:225], v190 offset:56320
	s_setprio 0
	s_add_i32 s48, s58, s3
	s_mov_b32 m0, s48
	v_lshl_add_u64 v[184:185], v[184:185], 0, s[14:15]
	global_load_lds_dwordx4 v[184:185], off
	s_add_i32 m0, s48, 0x2000
	s_add_u32 s48, s52, 0x80080
	v_lshl_add_u64 v[184:185], v[226:227], 0, s[14:15]
	s_addc_u32 s49, s53, 0
	s_add_i32 s52, s59, s3
	global_load_lds_dwordx4 v[184:185], off
	v_lshl_add_u64 v[184:185], s[48:49], 0, v[154:155]
	s_mov_b32 m0, s52
	s_nop 0
	global_load_lds_dwordx4 v[184:185], off
	v_lshl_add_u64 v[184:185], s[48:49], 0, v[158:159]
	s_add_i32 m0, s52, 0x2000
	s_nop 0
	global_load_lds_dwordx4 v[184:185], off
	v_lshl_add_u64 v[184:185], v[228:229], 0, s[14:15]
	s_mov_b32 m0, s66
	s_nop 0
	global_load_lds_dwordx4 v[184:185], off
	v_lshl_add_u64 v[184:185], v[230:231], 0, s[14:15]
	s_mov_b32 m0, s67
	s_nop 0
	global_load_lds_dwordx4 v[184:185], off
	s_waitcnt vmcnt(8) lgkmcnt(0)
	s_setprio 1
	s_barrier
	v_mfma_f32_16x16x32_bf16 v[60:63], v[128:131], v[194:197], v[60:63]
	v_mfma_f32_16x16x32_bf16 v[56:59], v[136:139], v[194:197], v[56:59]
	v_mfma_f32_16x16x32_bf16 v[44:47], v[128:131], v[202:205], v[44:47]
	v_mfma_f32_16x16x32_bf16 v[40:43], v[136:139], v[202:205], v[40:43]
	v_mfma_f32_16x16x32_bf16 v[28:31], v[128:131], v[210:213], v[28:31]
	v_mfma_f32_16x16x32_bf16 v[24:27], v[136:139], v[210:213], v[24:27]
	v_mfma_f32_16x16x32_bf16 v[12:15], v[128:131], v[218:221], v[12:15]
	v_mfma_f32_16x16x32_bf16 v[8:11], v[136:139], v[218:221], v[8:11]
	v_mfma_f32_16x16x32_bf16 v[60:63], v[132:135], v[198:201], v[60:63]
	v_mfma_f32_16x16x32_bf16 v[56:59], v[140:143], v[198:201], v[56:59]
	v_mfma_f32_16x16x32_bf16 v[44:47], v[132:135], v[206:209], v[44:47]
	v_mfma_f32_16x16x32_bf16 v[40:43], v[140:143], v[206:209], v[40:43]
	v_mfma_f32_16x16x32_bf16 v[28:31], v[132:135], v[214:217], v[28:31]
	v_mfma_f32_16x16x32_bf16 v[24:27], v[140:143], v[214:217], v[24:27]
	v_mfma_f32_16x16x32_bf16 v[12:15], v[132:135], v[222:225], v[12:15]
	v_mfma_f32_16x16x32_bf16 v[8:11], v[140:143], v[222:225], v[8:11]
	s_setprio 0
	s_setprio 1
	v_mfma_f32_16x16x32_bf16 v[52:55], v[144:147], v[194:197], v[52:55]
	v_mfma_f32_16x16x32_bf16 v[48:51], v[176:179], v[194:197], v[48:51]
	v_mfma_f32_16x16x32_bf16 v[36:39], v[144:147], v[202:205], v[36:39]
	v_mfma_f32_16x16x32_bf16 v[32:35], v[176:179], v[202:205], v[32:35]
	s_add_i32 s57, s57, 2
	v_mfma_f32_16x16x32_bf16 v[20:23], v[144:147], v[210:213], v[20:23]
	s_add_u32 s27, s27, 0x100
	v_mfma_f32_16x16x32_bf16 v[16:19], v[176:179], v[210:213], v[16:19]
	s_addc_u32 s56, s56, 0
	v_mfma_f32_16x16x32_bf16 v[4:7], v[144:147], v[218:221], v[4:7]
	s_cmp_gt_u32 s57, 29
	v_mfma_f32_16x16x32_bf16 v[0:3], v[176:179], v[218:221], v[0:3]
	s_mov_b64 s[48:49], s[50:51]
	v_mfma_f32_16x16x32_bf16 v[52:55], v[148:151], v[198:201], v[52:55]
	v_mfma_f32_16x16x32_bf16 v[48:51], v[180:183], v[198:201], v[48:51]
	v_mfma_f32_16x16x32_bf16 v[36:39], v[148:151], v[206:209], v[36:39]
	v_mfma_f32_16x16x32_bf16 v[32:35], v[180:183], v[206:209], v[32:35]
	v_mfma_f32_16x16x32_bf16 v[20:23], v[148:151], v[214:217], v[20:23]
	v_mfma_f32_16x16x32_bf16 v[16:19], v[180:183], v[214:217], v[16:19]
	v_mfma_f32_16x16x32_bf16 v[4:7], v[148:151], v[222:225], v[4:7]
	v_mfma_f32_16x16x32_bf16 v[0:3], v[180:183], v[222:225], v[0:3]
	s_barrier
	s_setprio 0
	s_cbranch_scc0 .LBB0_146
	s_and_b64 vcc, exec, s[18:19]
	s_cbranch_vccz .LBB0_149
	s_barrier

.LBB0_672:
	ds_read_b128 v[128:131], v185
	ds_read_b128 v[132:135], v185 offset:1024
	ds_read_b128 v[136:139], v185 offset:2048
	ds_read_b128 v[140:143], v185 offset:3072
	ds_read_b128 v[162:165], v186
	ds_read_b128 v[166:169], v186 offset:1024
	ds_read_b128 v[170:173], v186 offset:2048
	ds_read_b128 v[174:177], v186 offset:3072
	ds_read_b128 v[178:181], v188
	ds_read_b128 v[192:195], v188 offset:1024
	ds_read_b128 v[196:199], v188 offset:2048
	ds_read_b128 v[200:203], v188 offset:3072
	ds_read_b128 v[204:207], v188 offset:4096
	ds_read_b128 v[208:211], v188 offset:5120
	ds_read_b128 v[212:215], v188 offset:6144
	ds_read_b128 v[216:219], v188 offset:7168
	s_add_u32 s38, s6, 0xfff80080
	s_addc_u32 s39, s7, -1
	s_cmp_eq_u32 s56, 28
	s_cselect_b32 s41, s27, s39
	s_cselect_b32 s40, s26, s38
	s_cselect_b32 s39, s23, s25
	s_cselect_b32 s38, s22, s5
	s_add_i32 m0, s42, 0xc000
	v_lshl_add_u64 v[182:183], s[6:7], 0, v[158:159]
	global_load_lds_dwordx4 v[182:183], off
	v_lshl_add_u64 v[182:183], s[6:7], 0, v[160:161]
	s_add_i32 m0, s42, 0xe000
	s_nop 0
	global_load_lds_dwordx4 v[182:183], off
	s_waitcnt vmcnt(8) lgkmcnt(0)
	s_setprio 1
	s_barrier
	v_mfma_f32_16x16x32_bf16 v[124:127], v[128:131], v[178:181], v[124:127]
	v_mfma_f32_16x16x32_bf16 v[120:123], v[136:139], v[178:181], v[120:123]
	v_mfma_f32_16x16x32_bf16 v[108:111], v[128:131], v[196:199], v[108:111]
	v_mfma_f32_16x16x32_bf16 v[104:107], v[136:139], v[196:199], v[104:107]
	v_mfma_f32_16x16x32_bf16 v[92:95], v[128:131], v[204:207], v[92:95]
	v_mfma_f32_16x16x32_bf16 v[88:91], v[136:139], v[204:207], v[88:91]
	v_mfma_f32_16x16x32_bf16 v[76:79], v[128:131], v[212:215], v[76:79]
	v_mfma_f32_16x16x32_bf16 v[72:75], v[136:139], v[212:215], v[72:75]
	v_mfma_f32_16x16x32_bf16 v[124:127], v[132:135], v[192:195], v[124:127]
	v_mfma_f32_16x16x32_bf16 v[120:123], v[140:143], v[192:195], v[120:123]
	v_mfma_f32_16x16x32_bf16 v[108:111], v[132:135], v[200:203], v[108:111]
	v_mfma_f32_16x16x32_bf16 v[104:107], v[140:143], v[200:203], v[104:107]
	v_mfma_f32_16x16x32_bf16 v[92:95], v[132:135], v[208:211], v[92:95]
	v_mfma_f32_16x16x32_bf16 v[88:91], v[140:143], v[208:211], v[88:91]
	v_mfma_f32_16x16x32_bf16 v[76:79], v[132:135], v[216:219], v[76:79]
	v_mfma_f32_16x16x32_bf16 v[72:75], v[140:143], v[216:219], v[72:75]
	s_setprio 0
	s_setprio 1
	v_mfma_f32_16x16x32_bf16 v[116:119], v[162:165], v[178:181], v[116:119]
	v_mfma_f32_16x16x32_bf16 v[112:115], v[170:173], v[178:181], v[112:115]
	v_mfma_f32_16x16x32_bf16 v[100:103], v[162:165], v[196:199], v[100:103]
	v_mfma_f32_16x16x32_bf16 v[96:99], v[170:173], v[196:199], v[96:99]
	v_mfma_f32_16x16x32_bf16 v[84:87], v[162:165], v[204:207], v[84:87]
	v_mfma_f32_16x16x32_bf16 v[80:83], v[170:173], v[204:207], v[80:83]
	v_mfma_f32_16x16x32_bf16 v[68:71], v[162:165], v[212:215], v[68:71]
	v_mfma_f32_16x16x32_bf16 v[64:67], v[170:173], v[212:215], v[64:67]
	v_mfma_f32_16x16x32_bf16 v[116:119], v[166:169], v[192:195], v[116:119]
	v_mfma_f32_16x16x32_bf16 v[112:115], v[174:177], v[192:195], v[112:115]
	v_mfma_f32_16x16x32_bf16 v[100:103], v[166:169], v[200:203], v[100:103]
	v_mfma_f32_16x16x32_bf16 v[96:99], v[174:177], v[200:203], v[96:99]
	v_mfma_f32_16x16x32_bf16 v[84:87], v[166:169], v[208:211], v[84:87]
	v_mfma_f32_16x16x32_bf16 v[80:83], v[174:177], v[208:211], v[80:83]
	v_mfma_f32_16x16x32_bf16 v[68:71], v[166:169], v[216:219], v[68:71]
	v_mfma_f32_16x16x32_bf16 v[64:67], v[174:177], v[216:219], v[64:67]
	s_barrier
	ds_read_b128 v[178:181], v188 offset:16384
	ds_read_b128 v[192:195], v188 offset:17408
	ds_read_b128 v[196:199], v188 offset:18432
	ds_read_b128 v[200:203], v188 offset:19456
	ds_read_b128 v[204:207], v188 offset:20480
	ds_read_b128 v[208:211], v188 offset:21504
	ds_read_b128 v[212:215], v188 offset:22528
	ds_read_b128 v[216:219], v188 offset:23552
	s_setprio 0
	s_add_i32 s57, s51, s35
	s_mov_b32 m0, s57
	v_lshl_add_u64 v[182:183], s[38:39], 0, v[148:149]
	global_load_lds_dwordx4 v[182:183], off
	s_add_i32 m0, s57, 0x2000
	s_add_u32 s58, s38, 0x80000
	v_lshl_add_u64 v[220:221], s[38:39], 0, v[144:145]
	s_addc_u32 s59, s39, 0
	s_add_i32 s57, s52, s35
	global_load_lds_dwordx4 v[220:221], off
	v_lshl_add_u64 v[222:223], s[58:59], 0, v[148:149]
	s_mov_b32 m0, s57
	v_lshl_add_u64 v[224:225], s[40:41], 0, v[146:147]
	global_load_lds_dwordx4 v[222:223], off
	v_lshl_add_u64 v[222:223], s[58:59], 0, v[144:145]
	s_add_i32 m0, s57, 0x2000
	s_nop 0
	global_load_lds_dwordx4 v[222:223], off
	v_lshl_add_u64 v[222:223], s[40:41], 0, v[150:151]
	s_mov_b32 m0, s42
	s_nop 0
	global_load_lds_dwordx4 v[222:223], off
	s_mov_b32 m0, s43
	s_nop 0
	global_load_lds_dwordx4 v[224:225], off
	s_waitcnt vmcnt(8) lgkmcnt(0)
	s_setprio 1
	s_barrier
	v_mfma_f32_16x16x32_bf16 v[60:63], v[128:131], v[178:181], v[60:63]
	v_mfma_f32_16x16x32_bf16 v[56:59], v[136:139], v[178:181], v[56:59]
	v_mfma_f32_16x16x32_bf16 v[44:47], v[128:131], v[196:199], v[44:47]
	v_mfma_f32_16x16x32_bf16 v[40:43], v[136:139], v[196:199], v[40:43]
	v_mfma_f32_16x16x32_bf16 v[28:31], v[128:131], v[204:207], v[28:31]
	v_mfma_f32_16x16x32_bf16 v[24:27], v[136:139], v[204:207], v[24:27]
	v_mfma_f32_16x16x32_bf16 v[12:15], v[128:131], v[212:215], v[12:15]
	v_mfma_f32_16x16x32_bf16 v[8:11], v[136:139], v[212:215], v[8:11]
	v_mfma_f32_16x16x32_bf16 v[60:63], v[132:135], v[192:195], v[60:63]
	v_mfma_f32_16x16x32_bf16 v[56:59], v[140:143], v[192:195], v[56:59]
	v_mfma_f32_16x16x32_bf16 v[44:47], v[132:135], v[200:203], v[44:47]
	v_mfma_f32_16x16x32_bf16 v[40:43], v[140:143], v[200:203], v[40:43]
	v_mfma_f32_16x16x32_bf16 v[28:31], v[132:135], v[208:211], v[28:31]
	v_mfma_f32_16x16x32_bf16 v[24:27], v[140:143], v[208:211], v[24:27]
	v_mfma_f32_16x16x32_bf16 v[12:15], v[132:135], v[216:219], v[12:15]
	v_mfma_f32_16x16x32_bf16 v[8:11], v[140:143], v[216:219], v[8:11]
	s_setprio 0
	s_setprio 1
	v_mfma_f32_16x16x32_bf16 v[52:55], v[162:165], v[178:181], v[52:55]
	v_mfma_f32_16x16x32_bf16 v[48:51], v[170:173], v[178:181], v[48:51]
	v_mfma_f32_16x16x32_bf16 v[36:39], v[162:165], v[196:199], v[36:39]
	v_mfma_f32_16x16x32_bf16 v[32:35], v[170:173], v[196:199], v[32:35]
	v_mfma_f32_16x16x32_bf16 v[20:23], v[162:165], v[204:207], v[20:23]
	v_mfma_f32_16x16x32_bf16 v[16:19], v[170:173], v[204:207], v[16:19]
	v_mfma_f32_16x16x32_bf16 v[4:7], v[162:165], v[212:215], v[4:7]
	v_mfma_f32_16x16x32_bf16 v[0:3], v[170:173], v[212:215], v[0:3]
	v_mfma_f32_16x16x32_bf16 v[52:55], v[166:169], v[192:195], v[52:55]
	v_mfma_f32_16x16x32_bf16 v[48:51], v[174:177], v[192:195], v[48:51]
	v_mfma_f32_16x16x32_bf16 v[36:39], v[166:169], v[200:203], v[36:39]
	v_mfma_f32_16x16x32_bf16 v[32:35], v[174:177], v[200:203], v[32:35]
	v_mfma_f32_16x16x32_bf16 v[20:23], v[166:169], v[208:211], v[20:23]
	v_mfma_f32_16x16x32_bf16 v[16:19], v[174:177], v[208:211], v[16:19]
	v_mfma_f32_16x16x32_bf16 v[4:7], v[166:169], v[216:219], v[4:7]
	v_mfma_f32_16x16x32_bf16 v[0:3], v[174:177], v[216:219], v[0:3]
	s_barrier
	s_setprio 0
.Lpeel_mid_p4:
	s_add_i32 s57, 0, 0x18000
	s_add_i32 s58, 0, 0x1c000
	v_add_u32_e32 v140, s57, v184
	v_add_u32_e32 v174, s58, v184
	ds_read_b128 v[128:131], v140
	ds_read_b128 v[132:135], v140 offset:1024
	ds_read_b128 v[136:139], v140 offset:2048
	ds_read_b128 v[140:143], v140 offset:3072
	ds_read_b128 v[162:165], v174
	ds_read_b128 v[166:169], v174 offset:1024
	ds_read_b128 v[170:173], v174 offset:2048
	ds_read_b128 v[174:177], v174 offset:3072
	s_add_u32 s40, s40, 0x80000
	s_addc_u32 s41, s41, 0
	s_mov_b32 m0, s44
	v_lshl_add_u64 v[226:227], s[40:41], 0, v[150:151]
	ds_read_b128 v[178:181], v188 offset:32768
	ds_read_b128 v[192:195], v188 offset:33792
	ds_read_b128 v[196:199], v188 offset:34816
	ds_read_b128 v[200:203], v188 offset:35840
	ds_read_b128 v[204:207], v188 offset:36864
	ds_read_b128 v[208:211], v188 offset:37888
	ds_read_b128 v[212:215], v188 offset:38912
	ds_read_b128 v[216:219], v188 offset:39936
	global_load_lds_dwordx4 v[226:227], off
	v_lshl_add_u64 v[226:227], s[40:41], 0, v[146:147]
	s_mov_b32 m0, s45
	s_nop 0
	global_load_lds_dwordx4 v[226:227], off
	s_waitcnt vmcnt(8) lgkmcnt(0)
	s_setprio 1
	s_barrier
	v_mfma_f32_16x16x32_bf16 v[124:127], v[128:131], v[178:181], v[124:127]
	v_mfma_f32_16x16x32_bf16 v[120:123], v[136:139], v[178:181], v[120:123]
	v_mfma_f32_16x16x32_bf16 v[108:111], v[128:131], v[196:199], v[108:111]
	v_mfma_f32_16x16x32_bf16 v[104:107], v[136:139], v[196:199], v[104:107]
	v_mfma_f32_16x16x32_bf16 v[92:95], v[128:131], v[204:207], v[92:95]
	v_mfma_f32_16x16x32_bf16 v[88:91], v[136:139], v[204:207], v[88:91]
	v_mfma_f32_16x16x32_bf16 v[76:79], v[128:131], v[212:215], v[76:79]
	v_mfma_f32_16x16x32_bf16 v[72:75], v[136:139], v[212:215], v[72:75]
	v_mfma_f32_16x16x32_bf16 v[124:127], v[132:135], v[192:195], v[124:127]
	v_mfma_f32_16x16x32_bf16 v[120:123], v[140:143], v[192:195], v[120:123]
	v_mfma_f32_16x16x32_bf16 v[108:111], v[132:135], v[200:203], v[108:111]
	v_mfma_f32_16x16x32_bf16 v[104:107], v[140:143], v[200:203], v[104:107]
	v_mfma_f32_16x16x32_bf16 v[92:95], v[132:135], v[208:211], v[92:95]
	v_mfma_f32_16x16x32_bf16 v[88:91], v[140:143], v[208:211], v[88:91]
	v_mfma_f32_16x16x32_bf16 v[76:79], v[132:135], v[216:219], v[76:79]
	v_mfma_f32_16x16x32_bf16 v[72:75], v[140:143], v[216:219], v[72:75]
	s_setprio 0
	s_setprio 1
	v_mfma_f32_16x16x32_bf16 v[116:119], v[162:165], v[178:181], v[116:119]
	v_mfma_f32_16x16x32_bf16 v[112:115], v[170:173], v[178:181], v[112:115]
	v_mfma_f32_16x16x32_bf16 v[100:103], v[162:165], v[196:199], v[100:103]
	v_mfma_f32_16x16x32_bf16 v[96:99], v[170:173], v[196:199], v[96:99]
	v_mfma_f32_16x16x32_bf16 v[84:87], v[162:165], v[204:207], v[84:87]
	v_mfma_f32_16x16x32_bf16 v[80:83], v[170:173], v[204:207], v[80:83]
	v_mfma_f32_16x16x32_bf16 v[68:71], v[162:165], v[212:215], v[68:71]
	v_mfma_f32_16x16x32_bf16 v[64:67], v[170:173], v[212:215], v[64:67]
	v_mfma_f32_16x16x32_bf16 v[116:119], v[166:169], v[192:195], v[116:119]
	v_mfma_f32_16x16x32_bf16 v[112:115], v[174:177], v[192:195], v[112:115]
	v_mfma_f32_16x16x32_bf16 v[100:103], v[166:169], v[200:203], v[100:103]
	v_mfma_f32_16x16x32_bf16 v[96:99], v[174:177], v[200:203], v[96:99]
	v_mfma_f32_16x16x32_bf16 v[84:87], v[166:169], v[208:211], v[84:87]
	v_mfma_f32_16x16x32_bf16 v[80:83], v[174:177], v[208:211], v[80:83]
	v_mfma_f32_16x16x32_bf16 v[68:71], v[166:169], v[216:219], v[68:71]
	v_mfma_f32_16x16x32_bf16 v[64:67], v[174:177], v[216:219], v[64:67]
	s_barrier
	ds_read_b128 v[178:181], v188 offset:49152
	ds_read_b128 v[192:195], v188 offset:50176
	ds_read_b128 v[196:199], v188 offset:51200
	ds_read_b128 v[200:203], v188 offset:52224
	ds_read_b128 v[204:207], v188 offset:53248
	ds_read_b128 v[208:211], v188 offset:54272
	ds_read_b128 v[212:215], v188 offset:55296
	ds_read_b128 v[216:219], v188 offset:56320
	s_setprio 0
	s_add_i32 s40, s57, s35
	s_mov_b32 m0, s40
	v_lshl_add_u64 v[182:183], v[182:183], 0, s[14:15]
	global_load_lds_dwordx4 v[182:183], off
	s_add_i32 m0, s40, 0x2000
	s_add_u32 s38, s38, 0x80080
	v_lshl_add_u64 v[182:183], v[220:221], 0, s[14:15]
	s_addc_u32 s39, s39, 0
	s_add_i32 s40, s58, s35
	global_load_lds_dwordx4 v[182:183], off
	v_lshl_add_u64 v[182:183], s[38:39], 0, v[148:149]
	s_mov_b32 m0, s40
	s_nop 0
	global_load_lds_dwordx4 v[182:183], off
	v_lshl_add_u64 v[182:183], s[38:39], 0, v[144:145]
	s_add_i32 m0, s40, 0x2000
	s_nop 0
	global_load_lds_dwordx4 v[182:183], off
	v_lshl_add_u64 v[182:183], v[222:223], 0, s[14:15]
	s_mov_b32 m0, s49
	s_nop 0
	global_load_lds_dwordx4 v[182:183], off
	v_lshl_add_u64 v[182:183], v[224:225], 0, s[14:15]
	s_mov_b32 m0, s50
	s_nop 0
	global_load_lds_dwordx4 v[182:183], off
	s_waitcnt vmcnt(8) lgkmcnt(0)
	s_setprio 1
	s_barrier
	v_mfma_f32_16x16x32_bf16 v[60:63], v[128:131], v[178:181], v[60:63]
	v_mfma_f32_16x16x32_bf16 v[56:59], v[136:139], v[178:181], v[56:59]
	v_mfma_f32_16x16x32_bf16 v[44:47], v[128:131], v[196:199], v[44:47]
	v_mfma_f32_16x16x32_bf16 v[40:43], v[136:139], v[196:199], v[40:43]
	v_mfma_f32_16x16x32_bf16 v[28:31], v[128:131], v[204:207], v[28:31]
	v_mfma_f32_16x16x32_bf16 v[24:27], v[136:139], v[204:207], v[24:27]
	v_mfma_f32_16x16x32_bf16 v[12:15], v[128:131], v[212:215], v[12:15]
	v_mfma_f32_16x16x32_bf16 v[8:11], v[136:139], v[212:215], v[8:11]
	v_mfma_f32_16x16x32_bf16 v[60:63], v[132:135], v[192:195], v[60:63]
	v_mfma_f32_16x16x32_bf16 v[56:59], v[140:143], v[192:195], v[56:59]
	v_mfma_f32_16x16x32_bf16 v[44:47], v[132:135], v[200:203], v[44:47]
	v_mfma_f32_16x16x32_bf16 v[40:43], v[140:143], v[200:203], v[40:43]
	v_mfma_f32_16x16x32_bf16 v[28:31], v[132:135], v[208:211], v[28:31]
	v_mfma_f32_16x16x32_bf16 v[24:27], v[140:143], v[208:211], v[24:27]
	v_mfma_f32_16x16x32_bf16 v[12:15], v[132:135], v[216:219], v[12:15]
	v_mfma_f32_16x16x32_bf16 v[8:11], v[140:143], v[216:219], v[8:11]
	s_setprio 0
	s_setprio 1
	v_mfma_f32_16x16x32_bf16 v[52:55], v[162:165], v[178:181], v[52:55]
	v_mfma_f32_16x16x32_bf16 v[48:51], v[170:173], v[178:181], v[48:51]
	v_mfma_f32_16x16x32_bf16 v[36:39], v[162:165], v[196:199], v[36:39]
	v_mfma_f32_16x16x32_bf16 v[32:35], v[170:173], v[196:199], v[32:35]
	s_add_i32 s56, s56, 2
	v_mfma_f32_16x16x32_bf16 v[20:23], v[162:165], v[204:207], v[20:23]
	s_add_u32 s6, s6, 0x100
	v_mfma_f32_16x16x32_bf16 v[16:19], v[170:173], v[204:207], v[16:19]
	s_addc_u32 s7, s7, 0
	v_mfma_f32_16x16x32_bf16 v[4:7], v[162:165], v[212:215], v[4:7]
	s_add_u32 s5, s5, 0x100
	v_mfma_f32_16x16x32_bf16 v[0:3], v[170:173], v[212:215], v[0:3]
	s_addc_u32 s25, s25, 0
	v_mfma_f32_16x16x32_bf16 v[52:55], v[166:169], v[192:195], v[52:55]
	s_cmp_gt_u32 s56, 29
	v_mfma_f32_16x16x32_bf16 v[48:51], v[174:177], v[192:195], v[48:51]
	v_mfma_f32_16x16x32_bf16 v[36:39], v[166:169], v[200:203], v[36:39]
	v_mfma_f32_16x16x32_bf16 v[32:35], v[174:177], v[200:203], v[32:35]
	v_mfma_f32_16x16x32_bf16 v[20:23], v[166:169], v[208:211], v[20:23]
	v_mfma_f32_16x16x32_bf16 v[16:19], v[174:177], v[208:211], v[16:19]
	v_mfma_f32_16x16x32_bf16 v[4:7], v[166:169], v[216:219], v[4:7]
	v_mfma_f32_16x16x32_bf16 v[0:3], v[174:177], v[216:219], v[0:3]
	s_barrier
	s_setprio 0
	s_cbranch_scc0 .LBB0_672
	s_and_b64 vcc, exec, s[18:19]
	s_cbranch_vccz .LBB0_675
	s_barrier
